# v37 + one static s_setprio 1 for waves 4-7 across the attention phase (reset to 0 at phase exit)
# baseline (speedup 1.0000x reference)
; #define LAS __attribute__((address_space(3)))
; DI AttnUnit attn_decode(int u) {
;     AttnUnit a; a.h = u & 7; a.g = (u >> 3) % 3; const int tt = u / 24;
;     int sg, S;
;     if (tt < 256) { a.tok0 = (tt >> 5) * 8192; sg = tt & 31; S = 8192; } else { const int t2 = tt - 256; a.tok0 = TP + (t2 >> 4) * 4096; sg = t2 & 15; S = 4096; }
;     a.dsh = 2 * a.g; a.L = S >> a.dsh; const int spp = a.L >> 8; a.p = sg / spp; a.l0 = (sg % spp) * 256;
;     return a;
; }
; DI void attn_phase(LAS unsigned char* lds, bf16_t* QKV, float* lse, int G, int bid) {
;     int tid_ = threadIdx.x; asm volatile("" : "+v"(tid_)); asm volatile("" : "+s"(bid)); const int tid = tid_, wid = __builtin_amdgcn_readfirstlane(tid >> 6), lane = tid & 63, fr = lane & 15, fq = lane >> 4;
;     LAS unsigned char* Ks = lds; LAS unsigned char* Vs = lds + AK_BYTES;
;     const int NU = (T / 256) * 24;
;     const int bi = wid >> 1, half = wid & 1;
;     u32x4 pk_[6], pv_[6]; bf16x8 pq_[2][2];
;     if (bid < NU) {
;         const AttnUnit a = attn_decode(bid);
;         const bf16_t* qb = QKV + (size_t)((a.g * 3) * 8 + a.h) * T * 64; const bf16_t* kb = qb + (size_t)8 * T * 64; const bf16_t* vb = kb + (size_t)8 * T * 64;
; #pragma unroll
;         for (int ps = 0; ps < 6; ++ps) { const int rr = ps * 64 + (tid >> 3), ch = tid & 7, l = a.l0 - 64 + rr;
;             u32x4 kv = {0u, 0u, 0u, 0u}, vv = kv;
;             if (l >= 0 && l < a.L) { const size_t tok = (size_t)a.tok0 + ((size_t)l << a.dsh) + a.p; kv = *(const u32x4*)(kb + tok * 64 + ch * 8); vv = *(const u32x4*)(vb + tok * 64 + ch * 8); }
;             pk_[ps] = kv; pv_[ps] = vv; }
.LBB0_344:
	s_or_b64 exec, exec, s[0:1]
	v_readfirstlane_b32 s2, v253
	s_nop 3
	s_lshr_b32 s2, s2, 6
	s_cmp_ge_u32 s2, 4
	s_cbranch_scc0 .Laprio_done
	s_setprio 1
.Laprio_done:
	v_writelane_b32 v254, s92, 62
	v_writelane_b32 v254, s68, 63
	v_mov_b32_e32 v54, v253
	s_mov_b32 s26, s92
	v_writelane_b32 v255, s69, 0
	v_writelane_b32 v255, s70, 1
	s_waitcnt lgkmcnt(0)
	s_barrier
	s_cmpk_gt_i32 s26, 0x23ff
	v_readfirstlane_b32 s6, v54
	v_writelane_b32 v255, s71, 2
	s_cbranch_scc1 .LBB0_378
	s_mul_hi_i32 s0, s26, 0x2aaaaaab
	s_lshr_b32 s1, s0, 31
	s_ashr_i32 s0, s0, 2
	s_add_i32 s0, s0, s1
	s_lshl_b32 s1, s0, 8
	s_add_i32 s2, s1, 0x7fff0000
	s_and_b32 s2, s2, 0x7ffff000
	s_add_i32 s2, s2, 0x10000
	s_and_b32 s1, s1, 0xffffe000
	s_cmpk_lt_i32 s26, 0x1800
	s_cselect_b32 s3, 31, 15
	s_movk_i32 s4, 0x2000
	s_cselect_b32 s4, s4, 0x1000
	s_cselect_b32 s1, s1, s2
	s_cselect_b32 s2, 5, 4
	s_and_b32 s0, s3, s0
	s_ashr_i32 s3, s26, 3
	s_mul_hi_i32 s5, s3, 0x55555556
	s_lshr_b32 s7, s5, 31
	s_add_i32 s5, s5, s7
	s_mul_i32 s5, s5, 3
	s_sub_i32 s3, s3, s5
	s_lshl_b32 s7, s3, 1
	s_lshr_b32 s9, s4, s7
	s_lshr_b32 s4, s9, 8
	s_sub_i32 s2, s2, s7
	s_add_i32 s4, s4, -1
	s_and_b32 s5, s26, 7
	s_lshr_b32 s2, s0, s2
	s_and_b32 s0, s4, s0
	s_mul_i32 s3, s3, 24
	s_lshl_b32 s8, s0, 8
	s_or_b32 s0, s3, s5
	s_mul_hi_i32 s3, s0, 0xc00000
	s_mul_i32 s0, s0, 0xc00000
	v_readlane_b32 s4, v255, 3
	v_lshlrev_b32_e32 v55, 3, v54
	v_readlane_b32 s5, v255, 4
	s_add_u32 s4, s4, s0
	v_and_b32_e32 v1, 56, v55
	v_mov_b32_e32 v0, 0
	s_addc_u32 s5, s5, s3
	v_lshlrev_b32_e32 v132, 1, v1
	v_mov_b32_e32 v133, v0
	s_ashr_i32 s3, s1, 31
	s_or_b32 s2, s1, s2
	v_lshl_add_u64 v[2:3], s[4:5], 0, v[132:133]
	s_mov_b64 s[0:1], 0x6000000
	v_ashrrev_i32_e32 v138, 3, v54
	v_lshl_add_u64 v[24:25], v[2:3], 0, s[0:1]
	s_mov_b64 s[0:1], 0xc000000
	v_subrev_u32_e32 v139, 64, v138
	s_waitcnt vmcnt(5)
	v_lshl_add_u64 v[26:27], v[2:3], 0, s[0:1]
	v_mov_b32_e32 v2, v0
	v_mov_b32_e32 v3, v0
	v_add_u32_e32 v48, s8, v139
	v_mov_b32_e32 v1, v0
	v_mov_b64_e32 v[6:7], v[2:3]
	v_mov_b64_e32 v[10:11], v[2:3]
	v_cmp_gt_u32_e32 vcc, s9, v48
	v_mov_b64_e32 v[4:5], v[0:1]
	v_mov_b64_e32 v[8:9], v[0:1]
	s_and_saveexec_b64 s[0:1], vcc
	s_cbranch_execz .LBB0_347
	v_mov_b32_e32 v49, v0
	v_lshlrev_b64 v[4:5], s7, v[48:49]
	v_lshl_add_u64 v[4:5], v[4:5], 0, s[2:3]
	v_lshlrev_b64 v[4:5], 7, v[4:5]
	v_lshl_add_u64 v[14:15], v[24:25], 0, v[4:5]
	v_lshl_add_u64 v[12:13], v[26:27], 0, v[4:5]
	global_load_dwordx4 v[8:11], v[14:15], off
	global_load_dwordx4 v[4:7], v[12:13], off

; DI unsigned xb_ld(unsigned* p)              { return __hip_atomic_load(p, __ATOMIC_RELAXED, __HIP_MEMORY_SCOPE_AGENT); }
; DI void xcd_barrier_complete(unsigned* bar, unsigned x, unsigned& nloc, unsigned& nx) {
;     const unsigned G = gridDim.x * gridDim.y * gridDim.z;
;     unsigned sum, cnt, mine, sp = 0u;
;     for (;;) {
;         sum = 0u; cnt = 0u; mine = 0u;
; #pragma unroll
;         for (unsigned j = 0; j < 16; ++j) { const unsigned c = xb_ld(&bar[XB_XCNT(j)]); sum += c; cnt += (c > 0u) ? 1u : 0u; mine = (j == x) ? c : mine; }
;         if (sum == G) break;
;         __builtin_amdgcn_s_sleep(1);
;         if ((++sp & 255u) == 0u) { if (xb_ld(&bar[XB_TMO])) break; if (sp > XB_SPIN_CAP) { atomicAdd(&bar[XB_TMO], 1u); break; } }
; DI void xcd_barrier(const XcdBarrier& b) {
;     asm volatile("s_waitcnt vmcnt(0)" ::: "memory");
;     __syncthreads();
;     if (threadIdx.x == 0) {
;         unsigned* bar = b.bar;
;         __builtin_amdgcn_s_waitcnt(0);
;         unsigned nloc = b.st[0], nx = b.st[1];
;         if (nloc == 0u) { xcd_barrier_complete(bar, b.x, nloc, nx); b.st[0] = nloc; b.st[1] = nx; }
.LBB0_378:
	s_setprio 0
	s_waitcnt lgkmcnt(0)
	s_barrier
	s_waitcnt vmcnt(0)
	s_barrier
	s_mov_b64 s[0:1], exec
	v_readlane_b32 s2, v254, 20
	v_readlane_b32 s3, v254, 21
	s_and_b64 s[2:3], s[0:1], s[2:3]
	s_mov_b64 exec, s[2:3]
	s_cbranch_execz .LBB0_430
	s_add_i32 s2, 0, 0x23fc0
	v_mov_b32_e32 v0, s2
	s_waitcnt vmcnt(0) expcnt(0) lgkmcnt(0)
	ds_read_b32 v2, v0
	s_add_i32 s2, 0, 0x23fc4
	v_mov_b32_e32 v0, s2
	ds_read_b32 v0, v0
	s_waitcnt lgkmcnt(1)
	v_cmp_ne_u32_e32 vcc, 0, v2
	s_cbranch_vccnz .LBB0_394
	v_readlane_b32 s2, v254, 0
	s_mul_i32 s33, s71, s2
	s_add_u32 s2, s68, 0xc4200
	s_addc_u32 s3, s69, 0
	s_add_u32 s4, s68, 0xc4400
	s_addc_u32 s5, s69, 0
	s_add_u32 s6, s68, 0xc4500
	s_addc_u32 s7, s69, 0
	s_add_u32 s8, s68, 0xc4600
	s_addc_u32 s9, s69, 0
	s_add_u32 s10, s68, 0xc4700
	s_addc_u32 s11, s69, 0
	s_add_u32 s12, s68, 0xc4800
	s_addc_u32 s13, s69, 0
	s_add_u32 s14, s68, 0xc4900
	s_addc_u32 s15, s69, 0
	s_add_u32 s16, s68, 0xc4a00
	s_addc_u32 s17, s69, 0
	s_add_u32 s18, s68, 0xc4b00
	s_addc_u32 s19, s69, 0
	s_add_u32 s20, s68, 0xc4c00
	s_addc_u32 s21, s69, 0
	s_add_u32 s22, s68, 0xc4d00
	s_addc_u32 s23, s69, 0
	s_add_u32 s24, s68, 0xc4e00
	s_addc_u32 s25, s69, 0
	s_add_u32 s26, s68, 0xc4f00
	s_addc_u32 s27, s69, 0
	s_add_u32 s28, s68, 0xc5000
	s_addc_u32 s29, s69, 0
	s_add_u32 s30, s68, 0xc5100
	s_addc_u32 s31, s69, 0
	s_add_u32 s34, s68, 0xc5200
	s_addc_u32 s35, s69, 0
	s_add_u32 s36, s68, 0xc5300
	s_mul_i32 s33, s33, s70
	s_addc_u32 s37, s69, 0
	s_mov_b32 s44, 1
	v_mov_b32_e32 v16, 0
	s_branch .LBB0_382
